# ln_in_rows: first-iteration-only vmcnt waits moved to preheader; next-row prefetch waited at loop bottom
# baseline (speedup 1.0000x reference)
; DI int otid() { int t = __builtin_amdgcn_workitem_id_x(); asm volatile("" : "+v"(t)); return t; }
; DI unsigned pack2(float a, float b) { const f32x2 v = {a, b}; return __builtin_bit_cast(unsigned, __builtin_convertvector(v, bf16v2)); }
; DI float wsum(float v) { for (int o = 32; o; o >>= 1) v += __shfl_xor(v, o); return v; }
; DI void ln_in_rows(const float* __restrict__ src, const float* __restrict__ g, const float* __restrict__ bta, const float* __restrict__ w_in, u16* __restrict__ dst, float* __restrict__ G, float* Wg) {
;   const int lane = otid() & 63, wave = otid() >> 6;
;   for (int e = otid(); e < 8192; e += 512) Wg[e] = w_in[(size_t)(e >> 3) * 3592 + 3584 + (e & 7)];
;   __syncthreads();
;   float4 nv[4];
;   { const int row = blockIdx.x * 8 + wave; for (int i = 0; i < 4; ++i) nv[i] = *(const float4*)(src + (size_t)row * 1024 + i * 256 + lane * 4); }
;   for (int row = blockIdx.x * 8 + wave; row < T_TOK; row += gridDim.x * 8) {
;     float4 v[4];
;     float s = 0.f;
;     for (int i = 0; i < 4; ++i) { v[i] = nv[i]; s += v[i].x + v[i].y + v[i].z + v[i].w; }
;     { const int nrow = row + gridDim.x * 8; if (nrow < T_TOK) for (int i = 0; i < 4; ++i) nv[i] = *(const float4*)(src + (size_t)nrow * 1024 + i * 256 + lane * 4); }
;     const float mu = wsum(s) * (1.f / 1024.f);
;     float q = 0.f;
;     for (int i = 0; i < 4; ++i) { float a = v[i].x - mu, b = v[i].y - mu, c = v[i].z - mu, d = v[i].w - mu; q += a * a + b * b + c * c + d * d; }
;     const float rstd = rsqrtf(wsum(q) * (1.f / 1024.f) + LN_EPS);
;     float pg[8];
; #pragma unroll
;     for (int j = 0; j < 8; ++j) pg[j] = 0.f;
; #pragma unroll
;     for (int i = 0; i < 4; ++i) {
;       const int c0 = i * 256 + lane * 4;
;       float4 gg = *(const float4*)(g + c0), bb = *(const float4*)(bta + c0);
;       float y[4];
;       y[0] = (v[i].x - mu) * rstd * gg.x + bb.x; y[1] = (v[i].y - mu) * rstd * gg.y + bb.y; y[2] = (v[i].z - mu) * rstd * gg.z + bb.z; y[3] = (v[i].w - mu) * rstd * gg.w + bb.w;
;       uint2 o; o.x = pack2(y[0], y[1]); o.y = pack2(y[2], y[3]);
;       *(uint2*)(dst + (size_t)row * 1024 + c0) = o;
; #pragma unroll
;       for (int e = 0; e < 4; ++e) {
;         const float4 w0 = *(const float4*)(Wg + (c0 + e) * 8), w1 = *(const float4*)(Wg + (c0 + e) * 8 + 4);
.LBB0_165:
	s_or_b64 exec, exec, s[0:1]
	s_add_u32 s0, s68, 0x6300000
	s_addc_u32 s1, s69, 0
	v_writelane_b32 v250, s0, 19
	v_ashrrev_i32_e32 v1, 6, v1
	s_mov_b32 s2, 0x10000
	v_writelane_b32 v250, s1, 20
	s_lshl_b32 s1, s94, 3
	s_lshl_b32 s0, s70, 3
	s_add_u32 s24, s68, 0x6800000
	v_add_u32_e32 v194, s1, v1
	v_writelane_b32 v250, s0, 23
	s_addc_u32 s25, s69, 0
	v_cmp_gt_i32_e32 vcc, s2, v194
	s_waitcnt lgkmcnt(0)
	s_barrier
	v_writelane_b32 v250, s1, 27
	s_and_saveexec_b64 s[4:5], vcc
	s_cbranch_execz .LBB0_172
	v_ashrrev_i32_e32 v195, 31, v194
	v_and_b32_e32 v162, 63, v90
	v_lshlrev_b64 v[2:3], 12, v[194:195]
	v_mbcnt_hi_u32_b32 v34, -1, v203
	v_lshl_add_u64 v[2:3], s[52:53], 0, v[2:3]
	v_lshlrev_b32_e32 v196, 4, v162
	v_mov_b32_e32 v197, 0
	v_and_b32_e32 v1, 64, v34
	v_lshl_add_u64 v[2:3], v[2:3], 0, v[196:197]
	v_add_u32_e32 v35, 64, v1
	v_xor_b32_e32 v1, 32, v34
	global_load_dwordx4 v[178:181], v[2:3], off offset:3072
	global_load_dwordx4 v[182:185], v[2:3], off offset:2048
	global_load_dwordx4 v[186:189], v[2:3], off offset:1024
	global_load_dwordx4 v[190:193], v[2:3], off
	v_cmp_lt_i32_e32 vcc, v1, v35
	v_xor_b32_e32 v2, 16, v34
	v_xor_b32_e32 v36, 2, v34
	v_cndmask_b32_e32 v1, v34, v1, vcc
	v_cmp_lt_i32_e32 vcc, v2, v35
	v_readlane_b32 s0, v250, 19
	v_readlane_b32 s1, v250, 20
	v_cndmask_b32_e32 v2, v34, v2, vcc
	v_lshlrev_b32_e32 v205, 2, v2
	v_xor_b32_e32 v2, 8, v34
	v_cmp_lt_i32_e32 vcc, v2, v35
	v_and_b32_e32 v91, 32, v90
	v_lshrrev_b32_e32 v204, 3, v91
	v_cndmask_b32_e32 v2, v34, v2, vcc
	v_lshlrev_b32_e32 v207, 2, v2
	v_xor_b32_e32 v2, 4, v34
	v_cmp_lt_i32_e32 vcc, v2, v35
	v_lshl_add_u32 v158, v162, 7, 0
	v_lshl_add_u64 v[198:199], s[52:53], 0, v[196:197]
	v_cndmask_b32_e32 v2, v34, v2, vcc
	v_lshlrev_b32_e32 v209, 2, v2
	global_load_dwordx4 v[2:5], v196, s[56:57]
	global_load_dwordx4 v[6:9], v196, s[58:59]
	global_load_dwordx4 v[10:13], v196, s[56:57] offset:1024
	global_load_dwordx4 v[14:17], v196, s[58:59] offset:1024
	global_load_dwordx4 v[18:21], v196, s[56:57] offset:2048
	global_load_dwordx4 v[22:25], v196, s[58:59] offset:2048
	global_load_dwordx4 v[26:29], v196, s[56:57] offset:3072
	global_load_dwordx4 v[30:33], v196, s[58:59] offset:3072
	v_cmp_lt_i32_e32 vcc, v36, v35
	v_bfe_u32 v228, v90, 3, 1
	v_lshlrev_b32_e32 v162, 3, v162
	v_cndmask_b32_e32 v36, v34, v36, vcc
	v_lshlrev_b32_e32 v211, 2, v36
	v_xor_b32_e32 v36, 1, v34
	v_cmp_lt_i32_e32 vcc, v36, v35
	v_mov_b32_e32 v35, v197
	v_mov_b32_e32 v163, v197
	v_cndmask_b32_e32 v34, v34, v36, vcc
	v_lshlrev_b32_e32 v213, 2, v34
	v_and_b32_e32 v34, 7, v90
	v_cmp_eq_u32_e32 vcc, 0, v34
	v_bfe_u32 v34, v90, 1, 5
	v_lshl_add_u64 v[200:201], s[0:1], 0, v[34:35]
	v_cmp_eq_u32_e64 s[0:1], 0, v91
	v_and_b32_e32 v91, 16, v90
	v_lshrrev_b32_e32 v220, 3, v91
	v_cndmask_b32_e64 v202, 0, 4, s[0:1]
	v_cndmask_b32_e64 v206, 1, 5, s[0:1]
	v_cndmask_b32_e64 v208, 5, 1, s[0:1]
	v_cndmask_b32_e64 v210, 2, 6, s[0:1]
	v_cndmask_b32_e64 v212, 6, 2, s[0:1]
	v_cndmask_b32_e64 v214, 3, 7, s[0:1]
	v_cndmask_b32_e64 v216, 7, 3, s[0:1]
	v_cmp_eq_u32_e64 s[0:1], 0, v91
	v_lshrrev_b32_e32 v91, 3, v90
	ds_read_b128 v[34:37], v158
	ds_read_b128 v[38:41], v158 offset:16
	ds_read_b128 v[42:45], v158 offset:32
	ds_read_b128 v[46:49], v158 offset:48
	ds_read_b128 v[50:53], v158 offset:64
	ds_read_b128 v[54:57], v158 offset:80
	ds_read_b128 v[58:61], v158 offset:96
	ds_read_b128 v[62:65], v158 offset:112
	ds_read_b128 v[66:69], v158 offset:8192
	ds_read_b128 v[70:73], v158 offset:8208
	ds_read_b128 v[74:77], v158 offset:8224
	ds_read_b128 v[78:81], v158 offset:8240
	ds_read_b128 v[82:85], v158 offset:8256
	ds_read_b128 v[86:89], v158 offset:8272
	v_bitop3_b32 v196, v91, 1, v91 bitop3:0xc
	ds_read_b128 v[90:93], v158 offset:8288
	ds_read_b128 v[94:97], v158 offset:8304
	ds_read_b128 v[98:101], v158 offset:16384
	ds_read_b128 v[102:105], v158 offset:16400
	ds_read_b128 v[106:109], v158 offset:16416
	ds_read_b128 v[110:113], v158 offset:16432
	ds_read_b128 v[114:117], v158 offset:16448
	ds_read_b128 v[118:121], v158 offset:16464
	ds_read_b128 v[122:125], v158 offset:16480
	ds_read_b128 v[126:129], v158 offset:16496
	ds_read_b128 v[130:133], v158 offset:24576
	ds_read_b128 v[134:137], v158 offset:24592
	ds_read_b128 v[138:141], v158 offset:24608
	ds_read_b128 v[142:145], v158 offset:24624
	ds_read_b128 v[146:149], v158 offset:24640
	ds_read_b128 v[150:153], v158 offset:24656
	ds_read_b128 v[154:157], v158 offset:24672
	ds_read_b128 v[158:161], v158 offset:24688
	v_lshlrev_b32_e32 v1, 2, v1
	v_cndmask_b32_e64 v218, 0, 2, s[0:1]
	v_cndmask_b32_e64 v224, 1, 3, s[0:1]
	v_cndmask_b32_e64 v226, 3, 1, s[0:1]
	v_mov_b32_e32 v229, v197
	v_lshl_add_u64 v[230:231], s[24:25], 0, v[162:163]
	s_mov_b64 s[6:7], 0
	s_mov_b32 s3, 0xffff
	v_mov_b32_e32 v215, 0x3727c5ac
	s_mov_b32 s12, 0x800000
	s_waitcnt vmcnt(11)
	v_mov_b64_e32 v[174:175], v[178:179]
	s_waitcnt vmcnt(10)
	v_mov_b64_e32 v[170:171], v[182:183]
	s_waitcnt vmcnt(9)
	v_mov_b64_e32 v[166:167], v[186:187]
	s_waitcnt vmcnt(8)
	v_mov_b64_e32 v[162:163], v[190:191]
	v_mov_b64_e32 v[164:165], v[192:193]
	v_mov_b64_e32 v[168:169], v[188:189]
	v_mov_b64_e32 v[172:173], v[184:185]
	v_mov_b64_e32 v[176:177], v[180:181]
	s_waitcnt vmcnt(0)
	s_branch .LBB0_168
.LBB0_167:
	s_or_b64 exec, exec, s[8:9]
	s_waitcnt vmcnt(5)
	s_and_b64 s[0:1], exec, s[0:1]
	s_or_b64 s[6:7], s[0:1], s[6:7]
	v_mov_b32_e32 v194, v232
	v_mov_b64_e32 v[190:191], v[162:163]
	v_mov_b64_e32 v[192:193], v[164:165]
	v_mov_b64_e32 v[186:187], v[166:167]
	v_mov_b64_e32 v[188:189], v[168:169]
	v_mov_b64_e32 v[182:183], v[170:171]
	s_waitcnt lgkmcnt(0)
	v_mov_b64_e32 v[184:185], v[172:173]
	v_mov_b64_e32 v[178:179], v[174:175]
	v_mov_b64_e32 v[180:181], v[176:177]
	s_andn2_b64 exec, exec, s[6:7]
	s_cbranch_execz .LBB0_172

; DI unsigned pack2(float a, float b) { const f32x2 v = {a, b}; return __builtin_bit_cast(unsigned, __builtin_convertvector(v, bf16v2)); }
; DI float wsum(float v) { for (int o = 32; o; o >>= 1) v += __shfl_xor(v, o); return v; }
; DI void ln_in_rows(const float* __restrict__ src, const float* __restrict__ g, const float* __restrict__ bta, const float* __restrict__ w_in, u16* __restrict__ dst, float* __restrict__ G, float* Wg) {
;     ...
;     for (int i = 0; i < 4; ++i) { v[i] = nv[i]; s += v[i].x + v[i].y + v[i].z + v[i].w; }
;     { const int nrow = row + gridDim.x * 8; if (nrow < T_TOK) for (int i = 0; i < 4; ++i) nv[i] = *(const float4*)(src + (size_t)nrow * 1024 + i * 256 + lane * 4); }
;     const float mu = wsum(s) * (1.f / 1024.f);
;     float q = 0.f;
;     for (int i = 0; i < 4; ++i) { float a = v[i].x - mu, b = v[i].y - mu, c = v[i].z - mu, d = v[i].w - mu; q += a * a + b * b + c * c + d * d; }
;     const float rstd = rsqrtf(wsum(q) * (1.f / 1024.f) + LN_EPS);
;     float pg[8];
; #pragma unroll
;     for (int j = 0; j < 8; ++j) pg[j] = 0.f;
; #pragma unroll
;     for (int i = 0; i < 4; ++i) {
;       const int c0 = i * 256 + lane * 4;
;       float4 gg = *(const float4*)(g + c0), bb = *(const float4*)(bta + c0);
;       float y[4];
;       y[0] = (v[i].x - mu) * rstd * gg.x + bb.x; y[1] = (v[i].y - mu) * rstd * gg.y + bb.y; y[2] = (v[i].z - mu) * rstd * gg.z + bb.z; y[3] = (v[i].w - mu) * rstd * gg.w + bb.w;
;       uint2 o; o.x = pack2(y[0], y[1]); o.y = pack2(y[2], y[3]);
;       *(uint2*)(dst + (size_t)row * 1024 + c0) = o;
; #pragma unroll
;       for (int e = 0; e < 4; ++e) {
;         const float4 w0 = *(const float4*)(Wg + (c0 + e) * 8), w1 = *(const float4*)(Wg + (c0 + e) * 8 + 4);
;         pg[0] += y[e] * w0.x; pg[1] += y[e] * w0.y; pg[2] += y[e] * w0.z; pg[3] += y[e] * w0.w;
;         pg[4] += y[e] * w1.x; pg[5] += y[e] * w1.y; pg[6] += y[e] * w1.z; pg[7] += y[e] * w1.w;
.LBB0_170:
	s_or_b64 exec, exec, s[10:11]
	v_add_f32_e32 v195, v190, v191
	v_add_f32_e32 v195, v195, v192
	v_add_f32_e32 v217, v186, v187
	v_add_f32_e32 v195, v195, v193
	v_add_f32_e32 v217, v217, v188
	v_add_f32_e32 v195, 0, v195
	v_add_f32_e32 v217, v217, v189
	v_add_f32_e32 v195, v195, v217
	v_add_f32_e32 v217, v182, v183
	v_add_f32_e32 v217, v217, v184
	v_add_f32_e32 v217, v217, v185
	v_add_f32_e32 v195, v195, v217
	v_add_f32_e32 v217, v178, v179
	v_add_f32_e32 v217, v217, v180
	v_add_f32_e32 v217, v217, v181
	v_add_f32_e32 v195, v195, v217
	s_nop 1
	v_add_f32_dpp v195, v195, v195 row_shr:1 row_mask:0xf bank_mask:0xf
	s_nop 1
	v_add_f32_dpp v195, v195, v195 row_shr:2 row_mask:0xf bank_mask:0xf
	s_nop 1
	v_add_f32_dpp v195, v195, v195 row_shr:4 row_mask:0xf bank_mask:0xf
	s_nop 1
	v_add_f32_dpp v195, v195, v195 row_shr:8 row_mask:0xf bank_mask:0xf
	s_nop 1
	v_add_f32_dpp v195, v195, v195 row_bcast:15 row_mask:0xa bank_mask:0xf
	s_nop 1
	v_add_f32_dpp v195, v195, v195 row_bcast:31 row_mask:0xc bank_mask:0xf
	s_nop 0
	v_readlane_b32 s72, v195, 63
	s_nop 1
	v_mov_b32_e32 v195, s72
	v_mul_f32_e32 v234, 0x3a800000, v195
	v_pk_add_f32 v[190:191], v[190:191], v[234:235] op_sel_hi:[1,0] neg_lo:[0,1] neg_hi:[0,1]
	v_pk_add_f32 v[186:187], v[186:187], v[234:235] op_sel_hi:[1,0] neg_lo:[0,1] neg_hi:[0,1]
	v_mov_b32_e32 v240, v191
	v_mov_b32_e32 v241, v187
	v_pk_add_f32 v[192:193], v[192:193], v[234:235] op_sel_hi:[1,0] neg_lo:[0,1] neg_hi:[0,1]
	v_pk_add_f32 v[188:189], v[188:189], v[234:235] op_sel_hi:[1,0] neg_lo:[0,1] neg_hi:[0,1]
	v_pk_add_f32 v[182:183], v[182:183], v[234:235] op_sel_hi:[1,0] neg_lo:[0,1] neg_hi:[0,1]
	v_pk_add_f32 v[236:237], v[180:181], v[234:235] op_sel_hi:[1,0] neg_lo:[0,1] neg_hi:[0,1]
	v_pk_add_f32 v[180:181], v[178:179], v[234:235] op_sel_hi:[1,0] neg_lo:[0,1] neg_hi:[0,1]
	v_mov_b32_e32 v238, v190
	v_mov_b32_e32 v239, v186
	v_pk_mul_f32 v[240:241], v[240:241], v[240:241]
	v_mov_b32_e32 v178, v192
	v_mov_b32_e32 v179, v188
	v_pk_fma_f32 v[238:239], v[238:239], v[238:239], v[240:241]
	v_mov_b32_e32 v240, v181
	v_mov_b32_e32 v241, v183
	v_pk_add_f32 v[184:185], v[184:185], v[234:235] op_sel_hi:[1,0] neg_lo:[0,1] neg_hi:[0,1]
	v_pk_fma_f32 v[178:179], v[178:179], v[178:179], v[238:239]
	v_mov_b32_e32 v238, v180
	v_mov_b32_e32 v239, v182
	v_pk_mul_f32 v[240:241], v[240:241], v[240:241]
	v_mov_b32_e32 v234, v193
	v_mov_b32_e32 v235, v189
	v_mov_b32_e32 v242, v236
	v_mov_b32_e32 v243, v184
	v_pk_fma_f32 v[238:239], v[238:239], v[238:239], v[240:241]
	v_pk_fma_f32 v[178:179], v[234:235], v[234:235], v[178:179]
	v_mov_b32_e32 v234, v237
	v_mov_b32_e32 v235, v185
	v_pk_fma_f32 v[238:239], v[242:243], v[242:243], v[238:239]
	v_add_f32_e32 v178, v178, v179
	v_pk_fma_f32 v[234:235], v[234:235], v[234:235], v[238:239]
	v_ashrrev_i32_e32 v195, 31, v194
	v_add_f32_e32 v178, v235, v178
	v_add_f32_e32 v178, v234, v178
	s_nop 1
	v_add_f32_dpp v178, v178, v178 row_shr:1 row_mask:0xf bank_mask:0xf
	s_nop 1
	v_add_f32_dpp v178, v178, v178 row_shr:2 row_mask:0xf bank_mask:0xf
	s_nop 1
	v_add_f32_dpp v178, v178, v178 row_shr:4 row_mask:0xf bank_mask:0xf
	s_nop 1
	v_add_f32_dpp v178, v178, v178 row_shr:8 row_mask:0xf bank_mask:0xf
	s_nop 1
	v_add_f32_dpp v178, v178, v178 row_bcast:15 row_mask:0xa bank_mask:0xf
	s_nop 1
	v_add_f32_dpp v178, v178, v178 row_bcast:31 row_mask:0xc bank_mask:0xf
	s_nop 0
	v_readlane_b32 s73, v178, 63
	s_nop 1
	v_mov_b32_e32 v178, s73
	v_fmamk_f32 v178, v178, 0x3a800000, v215
	v_mul_f32_e32 v179, 0x4b800000, v178
	v_cmp_gt_f32_e64 s[8:9], s12, v178
	s_nop 1
	v_cndmask_b32_e64 v178, v178, v179, s[8:9]
	v_rsq_f32_e32 v217, v178
	v_lshlrev_b64 v[178:179], 11, v[194:195]
	v_lshl_add_u64 v[178:179], v[230:231], 0, v[178:179]
	v_mul_f32_e32 v219, 0x45800000, v217
	v_cndmask_b32_e64 v238, v217, v219, s[8:9]
	v_pk_mul_f32 v[190:191], v[190:191], v[238:239] op_sel_hi:[1,0]
	v_pk_mul_f32 v[234:235], v[192:193], v[238:239] op_sel_hi:[1,0]
	v_pk_mul_f32 v[182:183], v[182:183], v[238:239] op_sel_hi:[1,0]
	v_pk_fma_f32 v[192:193], v[2:3], v[190:191], v[6:7]
	v_pk_mul_f32 v[240:241], v[184:185], v[238:239] op_sel_hi:[1,0]
	v_pk_fma_f32 v[184:185], v[18:19], v[182:183], v[22:23]
	v_pk_mul_f32 v[182:183], v[236:237], v[238:239] op_sel_hi:[1,0]
	v_pk_fma_f32 v[236:237], v[34:35], v[192:193], 0 op_sel_hi:[1,0,0]
	v_pk_mul_f32 v[186:187], v[186:187], v[238:239] op_sel_hi:[1,0]
	v_pk_mul_f32 v[188:189], v[188:189], v[238:239] op_sel_hi:[1,0]
	v_pk_mul_f32 v[180:181], v[180:181], v[238:239] op_sel_hi:[1,0]
	v_pk_fma_f32 v[234:235], v[4:5], v[234:235], v[8:9]
	v_pk_fma_f32 v[236:237], v[42:43], v[192:193], v[236:237] op_sel:[0,1,0]
	v_pk_fma_f32 v[238:239], v[36:37], v[192:193], 0 op_sel_hi:[1,0,0]
	v_pk_fma_f32 v[236:237], v[50:51], v[234:235], v[236:237] op_sel_hi:[1,0,1]
	v_pk_fma_f32 v[238:239], v[44:45], v[192:193], v[238:239] op_sel:[0,1,0]
	v_pk_fma_f32 v[190:191], v[10:11], v[186:187], v[14:15]
	v_pk_fma_f32 v[186:187], v[20:21], v[240:241], v[24:25]
	v_pk_fma_f32 v[236:237], v[58:59], v[234:235], v[236:237] op_sel:[0,1,0]
	v_pk_fma_f32 v[238:239], v[52:53], v[234:235], v[238:239] op_sel_hi:[1,0,1]
	v_pk_fma_f32 v[240:241], v[38:39], v[192:193], 0 op_sel_hi:[1,0,0]
	v_pk_fma_f32 v[236:237], v[66:67], v[190:191], v[236:237] op_sel_hi:[1,0,1]
	v_pk_fma_f32 v[238:239], v[60:61], v[234:235], v[238:239] op_sel:[0,1,0]
	v_pk_fma_f32 v[240:241], v[46:47], v[192:193], v[240:241] op_sel:[0,1,0]
	v_pk_fma_f32 v[188:189], v[12:13], v[188:189], v[16:17]
	v_pk_fma_f32 v[236:237], v[74:75], v[190:191], v[236:237] op_sel:[0,1,0]
	v_pk_fma_f32 v[238:239], v[68:69], v[190:191], v[238:239] op_sel_hi:[1,0,1]
; DI unsigned pack2(float a, float b) { const f32x2 v = {a, b}; return __builtin_bit_cast(unsigned, __builtin_convertvector(v, bf16v2)); }
; DI void ln_in_rows(const float* __restrict__ src, const float* __restrict__ g, const float* __restrict__ bta, const float* __restrict__ w_in, u16* __restrict__ dst, float* __restrict__ G, float* Wg) {
;     ...
;     for (int i = 0; i < 4; ++i) {
;       const int c0 = i * 256 + lane * 4;
;       float4 gg = *(const float4*)(g + c0), bb = *(const float4*)(bta + c0);
;       float y[4];
;       y[0] = (v[i].x - mu) * rstd * gg.x + bb.x; y[1] = (v[i].y - mu) * rstd * gg.y + bb.y; y[2] = (v[i].z - mu) * rstd * gg.z + bb.z; y[3] = (v[i].w - mu) * rstd * gg.w + bb.w;
;       uint2 o; o.x = pack2(y[0], y[1]); o.y = pack2(y[2], y[3]);
;       *(uint2*)(dst + (size_t)row * 1024 + c0) = o;
; #pragma unroll
;       for (int e = 0; e < 4; ++e) {
;         const float4 w0 = *(const float4*)(Wg + (c0 + e) * 8), w1 = *(const float4*)(Wg + (c0 + e) * 8 + 4);
;         pg[0] += y[e] * w0.x; pg[1] += y[e] * w0.y; pg[2] += y[e] * w0.z; pg[3] += y[e] * w0.w;
;         pg[4] += y[e] * w1.x; pg[5] += y[e] * w1.y; pg[6] += y[e] * w1.z; pg[7] += y[e] * w1.w;
	v_pk_fma_f32 v[240:241], v[54:55], v[234:235], v[240:241] op_sel_hi:[1,0,1]
	v_pk_fma_f32 v[242:243], v[40:41], v[192:193], 0 op_sel_hi:[1,0,0]
	v_pk_fma_f32 v[236:237], v[82:83], v[188:189], v[236:237] op_sel_hi:[1,0,1]
	v_pk_fma_f32 v[238:239], v[76:77], v[190:191], v[238:239] op_sel:[0,1,0]
	v_pk_fma_f32 v[240:241], v[62:63], v[234:235], v[240:241] op_sel:[0,1,0]
	v_pk_fma_f32 v[242:243], v[48:49], v[192:193], v[242:243] op_sel:[0,1,0]
	v_pk_fma_f32 v[236:237], v[90:91], v[188:189], v[236:237] op_sel:[0,1,0]
	v_pk_fma_f32 v[238:239], v[84:85], v[188:189], v[238:239] op_sel_hi:[1,0,1]
	v_pk_fma_f32 v[240:241], v[70:71], v[190:191], v[240:241] op_sel_hi:[1,0,1]
	v_pk_fma_f32 v[242:243], v[56:57], v[234:235], v[242:243] op_sel_hi:[1,0,1]
	v_pk_fma_f32 v[236:237], v[98:99], v[184:185], v[236:237] op_sel_hi:[1,0,1]
	v_pk_fma_f32 v[238:239], v[92:93], v[188:189], v[238:239] op_sel:[0,1,0]
	v_pk_fma_f32 v[240:241], v[78:79], v[190:191], v[240:241] op_sel:[0,1,0]
	v_pk_fma_f32 v[242:243], v[64:65], v[234:235], v[242:243] op_sel:[0,1,0]
	v_pk_fma_f32 v[236:237], v[106:107], v[184:185], v[236:237] op_sel:[0,1,0]
	v_pk_fma_f32 v[238:239], v[100:101], v[184:185], v[238:239] op_sel_hi:[1,0,1]
	v_pk_fma_f32 v[240:241], v[86:87], v[188:189], v[240:241] op_sel_hi:[1,0,1]
	v_pk_fma_f32 v[242:243], v[72:73], v[190:191], v[242:243] op_sel_hi:[1,0,1]
	v_pk_fma_f32 v[236:237], v[114:115], v[186:187], v[236:237] op_sel_hi:[1,0,1]
	v_pk_fma_f32 v[238:239], v[108:109], v[184:185], v[238:239] op_sel:[0,1,0]
	v_pk_fma_f32 v[240:241], v[94:95], v[188:189], v[240:241] op_sel:[0,1,0]
	v_pk_fma_f32 v[242:243], v[80:81], v[190:191], v[242:243] op_sel:[0,1,0]
	v_pk_fma_f32 v[180:181], v[26:27], v[180:181], v[30:31]
	v_pk_fma_f32 v[236:237], v[122:123], v[186:187], v[236:237] op_sel:[0,1,0]
	v_pk_fma_f32 v[238:239], v[116:117], v[186:187], v[238:239] op_sel_hi:[1,0,1]
	v_pk_fma_f32 v[240:241], v[102:103], v[184:185], v[240:241] op_sel_hi:[1,0,1]
	v_pk_fma_f32 v[242:243], v[88:89], v[188:189], v[242:243] op_sel_hi:[1,0,1]
	v_pk_fma_f32 v[236:237], v[130:131], v[180:181], v[236:237] op_sel_hi:[1,0,1]
	v_pk_fma_f32 v[238:239], v[124:125], v[186:187], v[238:239] op_sel:[0,1,0]
	v_pk_fma_f32 v[240:241], v[110:111], v[184:185], v[240:241] op_sel:[0,1,0]
	v_pk_fma_f32 v[242:243], v[96:97], v[188:189], v[242:243] op_sel:[0,1,0]
	v_pk_fma_f32 v[182:183], v[28:29], v[182:183], v[32:33]
	v_pk_fma_f32 v[236:237], v[138:139], v[180:181], v[236:237] op_sel:[0,1,0]
	v_pk_fma_f32 v[238:239], v[132:133], v[180:181], v[238:239] op_sel_hi:[1,0,1]
	v_pk_fma_f32 v[240:241], v[118:119], v[186:187], v[240:241] op_sel_hi:[1,0,1]
	v_pk_fma_f32 v[242:243], v[104:105], v[184:185], v[242:243] op_sel_hi:[1,0,1]
	v_pk_fma_f32 v[236:237], v[146:147], v[182:183], v[236:237] op_sel_hi:[1,0,1]
	v_pk_fma_f32 v[238:239], v[140:141], v[180:181], v[238:239] op_sel:[0,1,0]
	v_pk_fma_f32 v[240:241], v[126:127], v[186:187], v[240:241] op_sel:[0,1,0]
	v_pk_fma_f32 v[242:243], v[112:113], v[184:185], v[242:243] op_sel:[0,1,0]
	v_pk_fma_f32 v[236:237], v[154:155], v[182:183], v[236:237] op_sel:[0,1,0]
	v_pk_fma_f32 v[238:239], v[148:149], v[182:183], v[238:239] op_sel_hi:[1,0,1]
	v_pk_fma_f32 v[240:241], v[180:181], v[134:135], v[240:241] op_sel_hi:[0,1,1]
	v_pk_fma_f32 v[242:243], v[120:121], v[186:187], v[242:243] op_sel_hi:[1,0,1]
	v_pk_fma_f32 v[238:239], v[156:157], v[182:183], v[238:239] op_sel:[0,1,0]
	v_pk_fma_f32 v[240:241], v[180:181], v[142:143], v[240:241] op_sel:[1,0,0]
	v_pk_fma_f32 v[242:243], v[128:129], v[186:187], v[242:243] op_sel:[0,1,0]
	v_pk_fma_f32 v[240:241], v[182:183], v[150:151], v[240:241] op_sel_hi:[0,1,1]
	v_pk_fma_f32 v[242:243], v[180:181], v[136:137], v[242:243] op_sel_hi:[0,1,1]
	v_pk_fma_f32 v[240:241], v[182:183], v[158:159], v[240:241] op_sel:[1,0,0]
	v_pk_fma_f32 v[242:243], v[180:181], v[144:145], v[242:243] op_sel:[1,0,0]
	v_pk_fma_f32 v[242:243], v[182:183], v[152:153], v[242:243] op_sel_hi:[0,1,1]
	v_pk_fma_f32 v[242:243], v[182:183], v[160:161], v[242:243] op_sel:[1,0,0]
	v_cvt_pk_bf16_f32 v192, v192, v193
	v_cvt_pk_bf16_f32 v193, v234, v235
	global_store_dwordx2 v[178:179], v[192:193], off
	v_cvt_pk_bf16_f32 v190, v190, v191
	v_cvt_pk_bf16_f32 v191, v188, v189
	v_cvt_pk_bf16_f32 v188, v184, v185
	v_cvt_pk_bf16_f32 v189, v186, v187
; DI void ln_in_rows(const float* __restrict__ src, const float* __restrict__ g, const float* __restrict__ bta, const float* __restrict__ w_in, u16* __restrict__ dst, float* __restrict__ G, float* Wg) {
;     ...
; #pragma unroll
;     for (int off = 32; off >= 8; off >>= 1) {
;       const bool up = (lane & off) != 0;
;       const int nkeep = off >> 3;
; #pragma unroll
;       for (int i = 0; i < 4; ++i) if (i < nkeep) {
;         const float send = up ? pg[i] : pg[i + nkeep];
;         const float keep = up ? pg[i + nkeep] : pg[i];
;         pg[i] = keep + __shfl_xor(send, off);
;       }
;     }
;     float tot = pg[0];
;     tot += __shfl_xor(tot, 4); tot += __shfl_xor(tot, 2); tot += __shfl_xor(tot, 1);
;     if ((lane & 7) == 0) G[(size_t)row * 8 + (lane >> 3)] = tot;
	v_cvt_pk_bf16_f32 v180, v180, v181
	v_cvt_pk_bf16_f32 v181, v182, v183
	global_store_dwordx2 v[178:179], v[190:191], off offset:512
	global_store_dwordx2 v[178:179], v[188:189], off offset:1024
	global_store_dwordx2 v[178:179], v[180:181], off offset:1536
	v_add_f32_dpp v236, v236, v236 row_shr:1 row_mask:0xf bank_mask:0xf
	v_add_f32_dpp v237, v237, v237 row_shr:1 row_mask:0xf bank_mask:0xf
	v_add_f32_dpp v238, v238, v238 row_shr:1 row_mask:0xf bank_mask:0xf
	v_add_f32_dpp v239, v239, v239 row_shr:1 row_mask:0xf bank_mask:0xf
	v_add_f32_dpp v240, v240, v240 row_shr:1 row_mask:0xf bank_mask:0xf
	v_add_f32_dpp v241, v241, v241 row_shr:1 row_mask:0xf bank_mask:0xf
	v_add_f32_dpp v242, v242, v242 row_shr:1 row_mask:0xf bank_mask:0xf
	v_add_f32_dpp v243, v243, v243 row_shr:1 row_mask:0xf bank_mask:0xf
	v_add_f32_dpp v236, v236, v236 row_shr:2 row_mask:0xf bank_mask:0xf
	v_add_f32_dpp v237, v237, v237 row_shr:2 row_mask:0xf bank_mask:0xf
	v_add_f32_dpp v238, v238, v238 row_shr:2 row_mask:0xf bank_mask:0xf
	v_add_f32_dpp v239, v239, v239 row_shr:2 row_mask:0xf bank_mask:0xf
	v_add_f32_dpp v240, v240, v240 row_shr:2 row_mask:0xf bank_mask:0xf
	v_add_f32_dpp v241, v241, v241 row_shr:2 row_mask:0xf bank_mask:0xf
	v_add_f32_dpp v242, v242, v242 row_shr:2 row_mask:0xf bank_mask:0xf
	v_add_f32_dpp v243, v243, v243 row_shr:2 row_mask:0xf bank_mask:0xf
	v_add_f32_dpp v236, v236, v236 row_shr:4 row_mask:0xf bank_mask:0xf
	v_add_f32_dpp v237, v237, v237 row_shr:4 row_mask:0xf bank_mask:0xf
	v_add_f32_dpp v238, v238, v238 row_shr:4 row_mask:0xf bank_mask:0xf
	v_add_f32_dpp v239, v239, v239 row_shr:4 row_mask:0xf bank_mask:0xf
	v_add_f32_dpp v240, v240, v240 row_shr:4 row_mask:0xf bank_mask:0xf
	v_add_f32_dpp v241, v241, v241 row_shr:4 row_mask:0xf bank_mask:0xf
	v_add_f32_dpp v242, v242, v242 row_shr:4 row_mask:0xf bank_mask:0xf
	v_add_f32_dpp v243, v243, v243 row_shr:4 row_mask:0xf bank_mask:0xf
	v_add_f32_dpp v236, v236, v236 row_shr:8 row_mask:0xf bank_mask:0xf
	v_add_f32_dpp v237, v237, v237 row_shr:8 row_mask:0xf bank_mask:0xf
	v_add_f32_dpp v238, v238, v238 row_shr:8 row_mask:0xf bank_mask:0xf
	v_add_f32_dpp v239, v239, v239 row_shr:8 row_mask:0xf bank_mask:0xf
	v_add_f32_dpp v240, v240, v240 row_shr:8 row_mask:0xf bank_mask:0xf
	v_add_f32_dpp v241, v241, v241 row_shr:8 row_mask:0xf bank_mask:0xf
	v_add_f32_dpp v242, v242, v242 row_shr:8 row_mask:0xf bank_mask:0xf
	v_add_f32_dpp v243, v243, v243 row_shr:8 row_mask:0xf bank_mask:0xf
	v_add_f32_dpp v236, v236, v236 row_bcast:15 row_mask:0xa bank_mask:0xf
	v_add_f32_dpp v237, v237, v237 row_bcast:15 row_mask:0xa bank_mask:0xf
	v_add_f32_dpp v238, v238, v238 row_bcast:15 row_mask:0xa bank_mask:0xf
	v_add_f32_dpp v239, v239, v239 row_bcast:15 row_mask:0xa bank_mask:0xf
	v_add_f32_dpp v240, v240, v240 row_bcast:15 row_mask:0xa bank_mask:0xf
	v_add_f32_dpp v241, v241, v241 row_bcast:15 row_mask:0xa bank_mask:0xf
	v_add_f32_dpp v242, v242, v242 row_bcast:15 row_mask:0xa bank_mask:0xf
	v_add_f32_dpp v243, v243, v243 row_bcast:15 row_mask:0xa bank_mask:0xf
	v_add_f32_dpp v236, v236, v236 row_bcast:31 row_mask:0xc bank_mask:0xf
	v_add_f32_dpp v237, v237, v237 row_bcast:31 row_mask:0xc bank_mask:0xf
	v_add_f32_dpp v238, v238, v238 row_bcast:31 row_mask:0xc bank_mask:0xf
	v_add_f32_dpp v239, v239, v239 row_bcast:31 row_mask:0xc bank_mask:0xf
	v_add_f32_dpp v240, v240, v240 row_bcast:31 row_mask:0xc bank_mask:0xf
	v_add_f32_dpp v241, v241, v241 row_bcast:31 row_mask:0xc bank_mask:0xf
	v_add_f32_dpp v242, v242, v242 row_bcast:31 row_mask:0xc bank_mask:0xf
	v_add_f32_dpp v243, v243, v243 row_bcast:31 row_mask:0xc bank_mask:0xf
	v_readlane_b32 s72, v236, 63
	v_readlane_b32 s73, v237, 63
	v_readlane_b32 s74, v238, 63
	v_readlane_b32 s75, v239, 63
	v_readlane_b32 s76, v240, 63
	v_readlane_b32 s77, v241, 63
	v_readlane_b32 s78, v242, 63
	v_readlane_b32 s79, v243, 63
	v_writelane_b32 v217, s72, 0
	v_writelane_b32 v217, s73, 8
	v_writelane_b32 v217, s74, 16
	v_writelane_b32 v217, s75, 24
	v_writelane_b32 v217, s76, 32
	v_writelane_b32 v217, s77, 40
	v_writelane_b32 v217, s78, 48
	v_writelane_b32 v217, s79, 56
	s_and_saveexec_b64 s[8:9], vcc
	s_cbranch_execz .LBB0_167
	v_lshlrev_b64 v[178:179], 5, v[194:195]
	v_lshl_add_u64 v[178:179], v[200:201], 0, v[178:179]
	global_store_dword v[178:179], v217, off
	s_branch .LBB0_167
